# group barriers within one XCD (nx==1, checked at run time): skip the L2 write-back and the cross-XCD TOP/TOPGEN stage; acquire invalidate kept
# baseline (speedup 1.0000x reference)
; __device__ __forceinline__ unsigned xb_ld(unsigned* p)              { return __hip_atomic_load(p, __ATOMIC_RELAXED, __HIP_MEMORY_SCOPE_AGENT); }
; __device__ __forceinline__ unsigned xb_add(unsigned* p, unsigned v) { return __hip_atomic_fetch_add(p, v, __ATOMIC_RELAXED, __HIP_MEMORY_SCOPE_AGENT); }
; #define XB_SPIN(cond, bar) do { unsigned _sp = 0; while (cond) { __builtin_amdgcn_s_sleep(1); \
;     if ((++_sp & 255u) == 0u) { if (xb_ld(&(bar)[XB_TMO])) break; if (_sp > XB_SPIN_CAP) { atomicAdd(&(bar)[XB_TMO], 1u); break; } } } } while (0)
; __device__ __forceinline__ void xcd_barrier(const XcdBarrier& b) {
;     ...
;         if (old + 1u == (gen + 1u) * nloc) {
;             __builtin_amdgcn_fence(__ATOMIC_RELEASE, "agent");
;             asm volatile("s_waitcnt vmcnt(0)" ::: "memory");
;             const unsigned og = xb_add(&bar[XB_TOP], 1u);
;             const unsigned tg = og / nx;
;             if (og + 1u == (tg + 1u) * nx) xb_add(&bar[XB_TOPGEN], 1u);
;             else XB_SPIN(xb_ld(&bar[XB_TOPGEN]) == tg, bar);
.LBB0_498:
	s_andn2_saveexec_b64 s[8:9], s[8:9]
	s_cbranch_execz .LBB0_516
	s_mov_b64 s[8:9], exec
	s_waitcnt lgkmcnt(0)
	v_cmp_eq_u32_e32 vcc, 1, v0
	s_cbranch_vccnz .Lgb_skip_0
	buffer_wbl2 sc1
	s_waitcnt lgkmcnt(0)
	s_waitcnt vmcnt(0)
	v_mbcnt_lo_u32_b32 v1, s8, 0
	v_mbcnt_hi_u32_b32 v1, s9, v1
	v_cmp_eq_u32_e32 vcc, 0, v1
	s_and_saveexec_b64 s[12:13], vcc
	s_cbranch_execz .LBB0_501
	s_bcnt1_i32_b64 s8, s[8:9]
	v_mov_b32_e32 v2, 0x3000
	v_mov_b32_e32 v3, s8
	global_atomic_add v2, v2, v3, s[60:61] offset:1024 sc0

; __device__ __forceinline__ unsigned xb_ld(unsigned* p)              { return __hip_atomic_load(p, __ATOMIC_RELAXED, __HIP_MEMORY_SCOPE_AGENT); }
; __device__ __forceinline__ unsigned xb_add(unsigned* p, unsigned v) { return __hip_atomic_fetch_add(p, v, __ATOMIC_RELAXED, __HIP_MEMORY_SCOPE_AGENT); }
; #define XB_SPIN(cond, bar) do { unsigned _sp = 0; while (cond) { __builtin_amdgcn_s_sleep(1); \
;     if ((++_sp & 255u) == 0u) { if (xb_ld(&(bar)[XB_TMO])) break; if (_sp > XB_SPIN_CAP) { atomicAdd(&(bar)[XB_TMO], 1u); break; } } } } while (0)
; __device__ __forceinline__ void xcd_barrier(const XcdBarrier& b) {
;     ...
;         if (old + 1u == (gen + 1u) * nloc) {
;             __builtin_amdgcn_fence(__ATOMIC_RELEASE, "agent");
;             asm volatile("s_waitcnt vmcnt(0)" ::: "memory");
;             const unsigned og = xb_add(&bar[XB_TOP], 1u);
;             const unsigned tg = og / nx;
;             if (og + 1u == (tg + 1u) * nx) xb_add(&bar[XB_TOPGEN], 1u);
;             else XB_SPIN(xb_ld(&bar[XB_TOPGEN]) == tg, bar);
.LBB0_762:
	s_andn2_saveexec_b64 s[6:7], s[6:7]
	s_cbranch_execz .LBB0_788
	s_mov_b64 s[6:7], exec
	s_waitcnt lgkmcnt(0)
	v_cmp_eq_u32_e32 vcc, 1, v0
	s_cbranch_vccnz .Lgb_skip_1
	buffer_wbl2 sc1
	s_waitcnt lgkmcnt(0)
	s_waitcnt vmcnt(0)
	v_mbcnt_lo_u32_b32 v1, s6, 0
	v_mbcnt_hi_u32_b32 v1, s7, v1
	v_cmp_eq_u32_e32 vcc, 0, v1
	s_and_saveexec_b64 s[8:9], vcc
	s_cbranch_execz .LBB0_765
	s_bcnt1_i32_b64 s6, s[6:7]
	v_mov_b32_e32 v2, 0x3000
	v_mov_b32_e32 v3, s6
	global_atomic_add v2, v2, v3, s[60:61] offset:1024 sc0
